# v33: v32 + single monotonic counter per group barrier (no return atomics, no generation word) at out-proj->FF1, FF1->FF2, end of layer
# baseline (speedup 1.0000x reference)
; #define LAS __attribute__((address_space(3)))
; __device__ __forceinline__ unsigned xb_ld(unsigned* p)              { return __hip_atomic_load(p, __ATOMIC_RELAXED, __HIP_MEMORY_SCOPE_AGENT); }
; __device__ __forceinline__ unsigned xb_add(unsigned* p, unsigned v) { return __hip_atomic_fetch_add(p, v, __ATOMIC_RELAXED, __HIP_MEMORY_SCOPE_AGENT); }
; __device__ __forceinline__ unsigned xb_xcc_id() { return (unsigned)__builtin_amdgcn_s_getreg((3 << 11) | 20) & 0xFu; }
; #define XB_SPIN(cond, bar) do { unsigned _sp = 0; while (cond) { __builtin_amdgcn_s_sleep(1); \
;     if ((++_sp & 255u) == 0u) { if (xb_ld(&(bar)[XB_TMO])) break; if (_sp > XB_SPIN_CAP) { atomicAdd(&(bar)[XB_TMO], 1u); break; } } } } while (0)
; __device__ __forceinline__ void xcd_barrier(unsigned* bar, volatile LAS unsigned* st, bool is0) {
;     asm volatile("s_waitcnt vmcnt(0)" ::: "memory");
;     __syncthreads();
;     if (is0) {
;         __builtin_amdgcn_s_waitcnt(0);
;         const unsigned x = xb_xcc_id();
;         unsigned nloc = st[0], nx = st[1];
;         if (nloc == 0u) { xcd_barrier_complete(bar, x, nloc, nx); st[0] = nloc; st[1] = nx; }
;         const unsigned old = xb_add(&bar[XB_XSUB(x)], 1u);
;         const unsigned gen = old / nloc;
;         if (old + 1u == (gen + 1u) * nloc) {
;             __builtin_amdgcn_fence(__ATOMIC_RELEASE, "agent");
;             asm volatile("s_waitcnt vmcnt(0)" ::: "memory");
;             const unsigned og = xb_add(&bar[XB_TOP], 1u);
;             const unsigned tg = og / nx;
;             if (og + 1u == (tg + 1u) * nx) xb_add(&bar[XB_TOPGEN], 1u);
;             else XB_SPIN(xb_ld(&bar[XB_TOPGEN]) == tg, bar);
;             __builtin_amdgcn_fence(__ATOMIC_ACQUIRE, "agent");
;             xb_add(&bar[XB_XGEN(x)], 1u);
;             asm volatile("s_waitcnt vmcnt(0)" ::: "memory");
;         } else {
;             XB_SPIN(xb_ld(&bar[XB_XGEN(x)]) == gen, bar);
;             __builtin_amdgcn_fence(__ATOMIC_ACQUIRE, "agent");
;             asm volatile("s_waitcnt vmcnt(0)" ::: "memory");
;         }
;     }
;     __syncthreads();
; }
; __global__ void __launch_bounds__(512) fwd_megakernel(Args A) {
;     ...
;                          (float*)(ws + WS_XCH) + (size_t)(2 * l) * MTOK * 8, (unsigned*)(ws + WS_CTL) + 8192 + (2 * l) * 2048, (unsigned*)(ws + WS_CTL) + 2};
;             pg8::gemm_phase(lds, g, S, E, wv);
;             SEAM(P + 4);
.LBB0_816:
	v_readlane_b32 s0, v254, 45
	v_readlane_b32 s8, v251, 41
	s_or_b32 s0, s0, 6
	v_readlane_b32 s15, v251, 48
	v_readlane_b32 s14, v251, 47
	s_cmp_ge_i32 s0, s15
	v_readlane_b32 s1, v254, 46
	v_readlane_b32 s9, v251, 42
	v_readlane_b32 s10, v251, 43
	v_readlane_b32 s11, v251, 44
	v_readlane_b32 s12, v251, 45
	v_readlane_b32 s13, v251, 46
	s_cbranch_scc1 .LBB0_884
	v_readlane_b32 s0, v252, 13
	v_readlane_b32 s1, v252, 14
	s_mov_b64 s[2:3], -1
	s_and_b64 vcc, exec, s[0:1]
	s_cbranch_vccz .LBB0_871
	s_cmp_eq_u32 s100, 0
	s_cbranch_scc1 .Llb_orig_3
	s_waitcnt vmcnt(0) lgkmcnt(0)
	s_barrier
	s_cmp_lg_u32 s94, 0
	s_cbranch_scc1 .Llb_join_3
	s_mov_b64 exec, 1
	v_readlane_b32 s8, v251, 45
	v_readlane_b32 s9, v251, 46
	v_readlane_b32 s6, v251, 50
	v_readlane_b32 s13, v254, 57
	v_mov_b32_e32 v4, 1
	v_mov_b32_e32 v8, 0
	s_and_b32 s6, s6, 7
	s_lshl_b32 s6, s6, 6
	s_add_u32 s6, s6, 0x7a00
	s_add_u32 s10, s8, s6
	s_addc_u32 s11, s9, 0
	s_add_u32 s13, s13, 1
	s_lshl_b32 s13, s13, 5
	s_cmp_eq_u32 s100, 2
	s_cbranch_scc1 .Llb_arr_3
	buffer_wbl2 sc1
	s_waitcnt vmcnt(0)
.Llb_arr_3:
	global_atomic_add v8, v4, s[10:11]
	s_mov_b32 s17, 0
.Llb_w_3:
	global_load_dword v6, v8, s[10:11] sc1
	s_add_u32 s17, s17, 1
	s_waitcnt vmcnt(0)
	v_readfirstlane_b32 s15, v6
	s_cmp_ge_u32 s15, s13
	s_cbranch_scc1 .Llb_acq_3
	s_sleep 1
	s_cmp_lt_u32 s17, 0x400000
	s_cbranch_scc1 .Llb_w_3

; #define LAS __attribute__((address_space(3)))
; __device__ __forceinline__ unsigned xb_add(unsigned* p, unsigned v) { return __hip_atomic_fetch_add(p, v, __ATOMIC_RELAXED, __HIP_MEMORY_SCOPE_AGENT); }
; __device__ __forceinline__ unsigned xb_xcc_id() { return (unsigned)__builtin_amdgcn_s_getreg((3 << 11) | 20) & 0xFu; }
; __device__ __forceinline__ void xcd_barrier(unsigned* bar, volatile LAS unsigned* st, bool is0) {
;     asm volatile("s_waitcnt vmcnt(0)" ::: "memory");
;     __syncthreads();
;     if (is0) {
;         __builtin_amdgcn_s_waitcnt(0);
;         const unsigned x = xb_xcc_id();
;         unsigned nloc = st[0], nx = st[1];
;         if (nloc == 0u) { xcd_barrier_complete(bar, x, nloc, nx); st[0] = nloc; st[1] = nx; }
;         const unsigned old = xb_add(&bar[XB_XSUB(x)], 1u);
.Llb_join_3:
	s_mov_b64 s[2:3], 0
	s_barrier
	s_branch .Llb_after_3
.Llb_orig_3:
	v_mov_b32_e32 v0, v1
	s_waitcnt vmcnt(0)
	s_waitcnt vmcnt(0) lgkmcnt(0)
	v_mbcnt_lo_u32_b32 v0, -1, v0
	v_mbcnt_hi_u32_b32 v0, -1, v0
	v_or_b32_e32 v0, s94, v0
	v_cmp_eq_u32_e32 vcc, 0, v0
	s_barrier
	s_and_saveexec_b64 s[2:3], vcc
	s_cbranch_execz .LBB0_870
	v_readlane_b32 s1, v254, 35
	s_waitcnt vmcnt(0) expcnt(0) lgkmcnt(0)
	s_getreg_b32 s0, hwreg(HW_REG_XCC_ID, 0, 4)
	v_mov_b32_e32 v0, s1
	ds_read_b32 v3, v0
	v_readlane_b32 s1, v254, 36
	s_and_b32 s0, s0, 15
	s_waitcnt lgkmcnt(0)
	v_cmp_ne_u32_e32 vcc, 0, v3
	v_mov_b32_e32 v0, s1
	ds_read_b32 v2, v0
	s_cbranch_vccnz .LBB0_834
	s_mov_b32 s1, 1
	s_branch .LBB0_822

; #define LAS __attribute__((address_space(3)))
; __device__ __forceinline__ unsigned xb_ld(unsigned* p)              { return __hip_atomic_load(p, __ATOMIC_RELAXED, __HIP_MEMORY_SCOPE_AGENT); }
; __device__ __forceinline__ unsigned xb_add(unsigned* p, unsigned v) { return __hip_atomic_fetch_add(p, v, __ATOMIC_RELAXED, __HIP_MEMORY_SCOPE_AGENT); }
; __device__ __forceinline__ unsigned xb_xcc_id() { return (unsigned)__builtin_amdgcn_s_getreg((3 << 11) | 20) & 0xFu; }
; #define XB_SPIN(cond, bar) do { unsigned _sp = 0; while (cond) { __builtin_amdgcn_s_sleep(1); \
;     if ((++_sp & 255u) == 0u) { if (xb_ld(&(bar)[XB_TMO])) break; if (_sp > XB_SPIN_CAP) { atomicAdd(&(bar)[XB_TMO], 1u); break; } } } } while (0)
; #define SEAM(k) do { } while (0)
; #define SEAM(k) do { if (lo <= (k) && (k) + 1 < hi) { if (hi > 1000) grid.sync(); else xcd_barrier(xbar, xst, opaque_tid(wv) == 0); } } while (0)
; __device__ __forceinline__ void xcd_barrier(unsigned* bar, volatile LAS unsigned* st, bool is0) {
;     asm volatile("s_waitcnt vmcnt(0)" ::: "memory");
;     __syncthreads();
;     if (is0) {
;         __builtin_amdgcn_s_waitcnt(0);
;         const unsigned x = xb_xcc_id();
;         unsigned nloc = st[0], nx = st[1];
;         if (nloc == 0u) { xcd_barrier_complete(bar, x, nloc, nx); st[0] = nloc; st[1] = nx; }
;         const unsigned old = xb_add(&bar[XB_XSUB(x)], 1u);
;         const unsigned gen = old / nloc;
;         if (old + 1u == (gen + 1u) * nloc) {
;             __builtin_amdgcn_fence(__ATOMIC_RELEASE, "agent");
;             asm volatile("s_waitcnt vmcnt(0)" ::: "memory");
;             const unsigned og = xb_add(&bar[XB_TOP], 1u);
;             const unsigned tg = og / nx;
;             if (og + 1u == (tg + 1u) * nx) xb_add(&bar[XB_TOPGEN], 1u);
;             else XB_SPIN(xb_ld(&bar[XB_TOPGEN]) == tg, bar);
;             __builtin_amdgcn_fence(__ATOMIC_ACQUIRE, "agent");
;             xb_add(&bar[XB_XGEN(x)], 1u);
;             asm volatile("s_waitcnt vmcnt(0)" ::: "memory");
;         } else {
;             XB_SPIN(xb_ld(&bar[XB_XGEN(x)]) == gen, bar);
;             __builtin_amdgcn_fence(__ATOMIC_ACQUIRE, "agent");
;             asm volatile("s_waitcnt vmcnt(0)" ::: "memory");
;         }
;     }
;     __syncthreads();
; }
; __global__ void __launch_bounds__(512) fwd_megakernel(Args A) {
;     ...
;             SEAM(P + 6);
.LBB0_909:
	v_readlane_b32 s0, v254, 45
	v_readlane_b32 s8, v251, 41
	s_add_i32 s0, s0, 8
	v_readlane_b32 s15, v251, 48
	s_cmp_ge_i32 s0, s15
	v_readlane_b32 s1, v254, 46
	v_readlane_b32 s9, v251, 42
	v_readlane_b32 s10, v251, 43
	v_readlane_b32 s11, v251, 44
	v_readlane_b32 s12, v251, 45
	v_readlane_b32 s13, v251, 46
	v_readlane_b32 s14, v251, 47
	s_cbranch_scc1 .LBB0_976
	v_readlane_b32 s6, v252, 13
	v_readlane_b32 s7, v252, 14
	s_mov_b64 s[2:3], -1
	s_and_b64 vcc, exec, s[6:7]
	s_cbranch_vccz .LBB0_964
	s_cmp_eq_u32 s100, 0
	s_cbranch_scc1 .Llb_orig_4
	s_waitcnt vmcnt(0) lgkmcnt(0)
	s_barrier
	s_cmp_lg_u32 s94, 0
	s_cbranch_scc1 .Llb_join_4
	s_mov_b64 exec, 1
	v_readlane_b32 s8, v251, 45
	v_readlane_b32 s9, v251, 46
	v_readlane_b32 s6, v251, 50
	v_readlane_b32 s13, v254, 57
	v_mov_b32_e32 v4, 1
	v_mov_b32_e32 v8, 0
	s_and_b32 s6, s6, 7
	s_lshl_b32 s6, s6, 6
	s_add_u32 s6, s6, 0x7c00
	s_add_u32 s10, s8, s6
	s_addc_u32 s11, s9, 0
	s_add_u32 s13, s13, 1
	s_lshl_b32 s13, s13, 5
	s_cmp_eq_u32 s100, 2
	s_cbranch_scc1 .Llb_arr_4
	buffer_wbl2 sc1
	s_waitcnt vmcnt(0)

; #define LAS __attribute__((address_space(3)))
; __device__ __forceinline__ unsigned xb_add(unsigned* p, unsigned v) { return __hip_atomic_fetch_add(p, v, __ATOMIC_RELAXED, __HIP_MEMORY_SCOPE_AGENT); }
; __device__ __forceinline__ unsigned xb_xcc_id() { return (unsigned)__builtin_amdgcn_s_getreg((3 << 11) | 20) & 0xFu; }
; __device__ __forceinline__ void xcd_barrier(unsigned* bar, volatile LAS unsigned* st, bool is0) {
;     asm volatile("s_waitcnt vmcnt(0)" ::: "memory");
;     __syncthreads();
;     if (is0) {
;         __builtin_amdgcn_s_waitcnt(0);
;         const unsigned x = xb_xcc_id();
;         unsigned nloc = st[0], nx = st[1];
;         if (nloc == 0u) { xcd_barrier_complete(bar, x, nloc, nx); st[0] = nloc; st[1] = nx; }
;         const unsigned old = xb_add(&bar[XB_XSUB(x)], 1u);
.Llb_join_4:
	s_mov_b64 s[2:3], 0
	s_barrier
	s_branch .Llb_after_4
.Llb_orig_4:
	v_mov_b32_e32 v0, v1
	s_waitcnt vmcnt(0)
	s_waitcnt vmcnt(0) lgkmcnt(0)
	v_mbcnt_lo_u32_b32 v0, -1, v0
	v_mbcnt_hi_u32_b32 v0, -1, v0
	v_or_b32_e32 v0, s94, v0
	v_cmp_eq_u32_e32 vcc, 0, v0
	s_barrier
	s_and_saveexec_b64 s[2:3], vcc
	s_cbranch_execz .LBB0_963
	v_readlane_b32 s6, v254, 35
	s_waitcnt vmcnt(0) expcnt(0) lgkmcnt(0)
	s_getreg_b32 s1, hwreg(HW_REG_XCC_ID, 0, 4)
	v_mov_b32_e32 v0, s6
	ds_read_b32 v3, v0
	v_readlane_b32 s6, v254, 36
	s_and_b32 s1, s1, 15
	s_waitcnt lgkmcnt(0)
	v_cmp_ne_u32_e32 vcc, 0, v3
	v_mov_b32_e32 v0, s6
	ds_read_b32 v2, v0
	s_cbranch_vccnz .LBB0_927
	s_mov_b32 s12, 1
	s_branch .LBB0_915

; #define LAS __attribute__((address_space(3)))
; __device__ __forceinline__ unsigned xb_ld(unsigned* p)              { return __hip_atomic_load(p, __ATOMIC_RELAXED, __HIP_MEMORY_SCOPE_AGENT); }
; __device__ __forceinline__ unsigned xb_add(unsigned* p, unsigned v) { return __hip_atomic_fetch_add(p, v, __ATOMIC_RELAXED, __HIP_MEMORY_SCOPE_AGENT); }
; __device__ __forceinline__ unsigned xb_xcc_id() { return (unsigned)__builtin_amdgcn_s_getreg((3 << 11) | 20) & 0xFu; }
; #define XB_SPIN(cond, bar) do { unsigned _sp = 0; while (cond) { __builtin_amdgcn_s_sleep(1); \
;     if ((++_sp & 255u) == 0u) { if (xb_ld(&(bar)[XB_TMO])) break; if (_sp > XB_SPIN_CAP) { atomicAdd(&(bar)[XB_TMO], 1u); break; } } } } while (0)
; #define SEAM(k) do { } while (0)
; __device__ __forceinline__ void xcd_barrier(unsigned* bar, volatile LAS unsigned* st, bool is0) {
;     asm volatile("s_waitcnt vmcnt(0)" ::: "memory");
;     __syncthreads();
;     if (is0) {
;         __builtin_amdgcn_s_waitcnt(0);
;         const unsigned x = xb_xcc_id();
;         unsigned nloc = st[0], nx = st[1];
;         if (nloc == 0u) { xcd_barrier_complete(bar, x, nloc, nx); st[0] = nloc; st[1] = nx; }
;         const unsigned old = xb_add(&bar[XB_XSUB(x)], 1u);
;         const unsigned gen = old / nloc;
;         if (old + 1u == (gen + 1u) * nloc) {
;             __builtin_amdgcn_fence(__ATOMIC_RELEASE, "agent");
;             asm volatile("s_waitcnt vmcnt(0)" ::: "memory");
;             const unsigned og = xb_add(&bar[XB_TOP], 1u);
;             const unsigned tg = og / nx;
;             if (og + 1u == (tg + 1u) * nx) xb_add(&bar[XB_TOPGEN], 1u);
;             else XB_SPIN(xb_ld(&bar[XB_TOPGEN]) == tg, bar);
;             __builtin_amdgcn_fence(__ATOMIC_ACQUIRE, "agent");
;             xb_add(&bar[XB_XGEN(x)], 1u);
;             asm volatile("s_waitcnt vmcnt(0)" ::: "memory");
;         } else {
;             XB_SPIN(xb_ld(&bar[XB_XGEN(x)]) == gen, bar);
;             __builtin_amdgcn_fence(__ATOMIC_ACQUIRE, "agent");
;             asm volatile("s_waitcnt vmcnt(0)" ::: "memory");
;         }
;     }
;     __syncthreads();
; }
; __global__ void __launch_bounds__(512) fwd_megakernel(Args A) {
;     ...
;             pg8::gemm_phase(lds, g, S, E, wv);
;             SEAM(P + 7);
;         }
.LBB0_1242:
	v_readlane_b32 s0, v252, 13
	v_readlane_b32 s1, v252, 14
	s_mov_b64 s[2:3], -1
	s_and_b64 vcc, exec, s[0:1]
	s_cbranch_vccz .LBB0_1296
	s_cmp_eq_u32 s100, 0
	s_cbranch_scc1 .Llb_orig_5
	s_waitcnt vmcnt(0) lgkmcnt(0)
	s_barrier
	s_cmp_lg_u32 s94, 0
	s_cbranch_scc1 .Llb_join_5
	s_mov_b64 exec, 1
	v_readlane_b32 s8, v251, 45
	v_readlane_b32 s9, v251, 46
	v_readlane_b32 s6, v251, 50
	v_readlane_b32 s13, v254, 57
	v_mov_b32_e32 v4, 1
	v_mov_b32_e32 v8, 0
	s_and_b32 s6, s6, 7
	s_lshl_b32 s6, s6, 6
	s_add_u32 s6, s6, 0x7e00
	s_add_u32 s10, s8, s6
	s_addc_u32 s11, s9, 0
	s_add_u32 s13, s13, 1
	s_lshl_b32 s13, s13, 5
	s_cmp_eq_u32 s100, 2
	s_cbranch_scc1 .Llb_arr_5
	buffer_wbl2 sc1
	s_waitcnt vmcnt(0)

; #define LAS __attribute__((address_space(3)))
; __device__ __forceinline__ unsigned xb_ld(unsigned* p)              { return __hip_atomic_load(p, __ATOMIC_RELAXED, __HIP_MEMORY_SCOPE_AGENT); }
; __device__ __forceinline__ unsigned xb_add(unsigned* p, unsigned v) { return __hip_atomic_fetch_add(p, v, __ATOMIC_RELAXED, __HIP_MEMORY_SCOPE_AGENT); }
; __device__ __forceinline__ unsigned xb_xcc_id() { return (unsigned)__builtin_amdgcn_s_getreg((3 << 11) | 20) & 0xFu; }
; #define XB_SPIN(cond, bar) do { unsigned _sp = 0; while (cond) { __builtin_amdgcn_s_sleep(1); \
;     if ((++_sp & 255u) == 0u) { if (xb_ld(&(bar)[XB_TMO])) break; if (_sp > XB_SPIN_CAP) { atomicAdd(&(bar)[XB_TMO], 1u); break; } } } } while (0)
; #define SEAM(k) do { } while (0)
; __device__ __forceinline__ void xcd_barrier(unsigned* bar, volatile LAS unsigned* st, bool is0) {
;     asm volatile("s_waitcnt vmcnt(0)" ::: "memory");
;     __syncthreads();
;     if (is0) {
;         __builtin_amdgcn_s_waitcnt(0);
;         const unsigned x = xb_xcc_id();
;         unsigned nloc = st[0], nx = st[1];
;         if (nloc == 0u) { xcd_barrier_complete(bar, x, nloc, nx); st[0] = nloc; st[1] = nx; }
;         const unsigned old = xb_add(&bar[XB_XSUB(x)], 1u);
;         const unsigned gen = old / nloc;
;         if (old + 1u == (gen + 1u) * nloc) {
;             __builtin_amdgcn_fence(__ATOMIC_RELEASE, "agent");
;             asm volatile("s_waitcnt vmcnt(0)" ::: "memory");
;             const unsigned og = xb_add(&bar[XB_TOP], 1u);
;             const unsigned tg = og / nx;
;             if (og + 1u == (tg + 1u) * nx) xb_add(&bar[XB_TOPGEN], 1u);
;             else XB_SPIN(xb_ld(&bar[XB_TOPGEN]) == tg, bar);
;             __builtin_amdgcn_fence(__ATOMIC_ACQUIRE, "agent");
;             xb_add(&bar[XB_XGEN(x)], 1u);
;             asm volatile("s_waitcnt vmcnt(0)" ::: "memory");
;         } else {
;             XB_SPIN(xb_ld(&bar[XB_XGEN(x)]) == gen, bar);
;             __builtin_amdgcn_fence(__ATOMIC_ACQUIRE, "agent");
;             asm volatile("s_waitcnt vmcnt(0)" ::: "memory");
;         }
;     }
;     __syncthreads();
; }
; __global__ void __launch_bounds__(512) fwd_megakernel(Args A) {
;     ...
;             pg8::gemm_phase(lds, g, S, E, wv);
;             SEAM(P + 7);
;         }
.Llb_acq_5:
	v_readlane_b32 s18, v251, 45
	v_readlane_b32 s19, v251, 46
	v_readlane_b32 s12, v254, 57
	s_add_u32 s18, s18, 0x7800
	s_addc_u32 s19, s19, 0
	s_add_u32 s12, s12, 1
	s_mul_i32 s14, s12, 0x300
	s_mov_b32 s16, 0
.Ltot_w:
	global_load_dword v6, v8, s[18:19] sc1
	s_add_u32 s16, s16, 1
	s_waitcnt vmcnt(0)
	v_readfirstlane_b32 s15, v6
	s_cmp_ge_u32 s15, s14
	s_cbranch_scc1 .Ltot_done
	s_sleep 1
	s_cmp_lt_u32 s16, 0x400000
	s_cbranch_scc1 .Ltot_w
.Ltot_done:
	buffer_inv sc1
	s_waitcnt vmcnt(0)
.Llb_noinv_5:
	s_mov_b64 exec, -1
.Llb_join_5:
	s_mov_b64 s[2:3], 0
	s_barrier
	s_branch .Llb_after_5
.Llb_orig_5:
	v_mov_b32_e32 v0, v1
	s_waitcnt vmcnt(0)
	s_waitcnt vmcnt(0) lgkmcnt(0)
	v_mbcnt_lo_u32_b32 v0, -1, v0
	v_mbcnt_hi_u32_b32 v0, -1, v0
	v_or_b32_e32 v0, s94, v0
	v_cmp_eq_u32_e32 vcc, 0, v0
	s_barrier
	s_and_saveexec_b64 s[2:3], vcc
	s_cbranch_execz .LBB0_1295
	v_readlane_b32 s1, v254, 35
	s_waitcnt vmcnt(0) expcnt(0) lgkmcnt(0)
	s_getreg_b32 s0, hwreg(HW_REG_XCC_ID, 0, 4)
	v_mov_b32_e32 v0, s1
	ds_read_b32 v3, v0
	v_readlane_b32 s1, v254, 36
	s_and_b32 s0, s0, 15
	s_waitcnt lgkmcnt(0)
	v_cmp_ne_u32_e32 vcc, 0, v3
	v_mov_b32_e32 v0, s1
	ds_read_b32 v2, v0
	s_cbranch_vccnz .LBB0_1259
	s_mov_b32 s1, 1
	s_branch .LBB0_1247
